# v20: v19 + write-through stores and no L2 write-back at the barriers of the l0 token, qkv and mixer phases
# baseline (speedup 1.0000x reference)
.LBB0_646:
	s_cmpk_gt_i32 s6, 0x17ff
	s_mov_b64 s[22:23], -1
	s_cbranch_scc0 .LBB0_648
	ds_read_b64 v[2:3], v7 offset:80
	s_add_i32 s4, s6, 0xffffe800
	s_lshl_b64 s[22:23], s[4:5], 9
	s_waitcnt lgkmcnt(0)
	v_readfirstlane_b32 s4, v2
	v_readfirstlane_b32 s7, v3
	s_add_u32 s22, s4, s22
	s_addc_u32 s23, s7, s23
	global_load_dwordx2 v[2:3], v24, s[22:23]
	s_mov_b32 s7, s5
	s_lshl_b64 s[22:23], s[6:7], 8
	v_lshl_add_u64 v[4:5], v[8:9], 0, s[22:23]
	s_mov_b64 s[22:23], 0
	s_waitcnt vmcnt(0)
	v_cvt_pk_bf16_f32 v2, v2, v3
	global_store_dword v[4:5], v2, off sc1

.LBB0_651:
	s_or_b64 exec, exec, s[24:25]
	ds_read_b128 v[26:29], v7 offset:224
	s_waitcnt vmcnt(1)
	v_pk_mul_f32 v[34:35], v[2:3], v[2:3]
	s_waitcnt vmcnt(0)
	v_pk_mul_f32 v[36:37], v[22:23], v[22:23]
	v_add_f32_e32 v34, v34, v35
	v_add_f32_e32 v35, v36, v37
	s_waitcnt lgkmcnt(0)
	v_readfirstlane_b32 s24, v26
	v_readfirstlane_b32 s25, v27
	v_pk_mul_f32 v[26:27], v[4:5], v[4:5]
	s_nop 0
	v_add_f32_e32 v26, v26, v34
	v_add_f32_dpp v34, v35, v35 quad_perm:[1,0,3,2] row_mask:0xf bank_mask:0xf bound_ctrl:1
	v_add_f32_e32 v26, v27, v26
	v_mov_b64_e32 v[30:31], v[200:201]
	v_mov_b64_e32 v[32:33], v[202:203]
	v_add_f32_dpp v27, v34, v34 quad_perm:[2,3,0,1] row_mask:0xf bank_mask:0xf bound_ctrl:1
	v_add_f32_dpp v26, v26, v26 quad_perm:[1,0,3,2] row_mask:0xf bank_mask:0xf bound_ctrl:1
	s_nop 0
	v_add_f32_dpp v27, v27, v27 row_half_mirror row_mask:0xf bank_mask:0xf bound_ctrl:1
	v_add_f32_dpp v26, v26, v26 quad_perm:[2,3,0,1] row_mask:0xf bank_mask:0xf bound_ctrl:1
	s_nop 0
	v_add_f32_dpp v27, v27, v27 row_mirror row_mask:0xf bank_mask:0xf bound_ctrl:1
	v_add_f32_dpp v26, v26, v26 row_half_mirror row_mask:0xf bank_mask:0xf bound_ctrl:1
	v_readlane_b32 s4, v27, 16
	v_readlane_b32 s7, v27, 48
	v_add_f32_dpp v34, v26, v26 row_mirror row_mask:0xf bank_mask:0xf bound_ctrl:1
	v_readlane_b32 s24, v27, 0
	v_readlane_b32 s25, v27, 32
	v_mov_b32_e32 v26, s4
	v_mov_b32_e32 v27, s7
	v_readlane_b32 s4, v34, 16
	v_readlane_b32 s7, v34, 48
	v_readlane_b32 s26, v34, 0
	v_readlane_b32 s27, v34, 32
	v_mov_b32_e32 v34, s4
	v_mov_b32_e32 v35, s7
	v_pk_add_f32 v[26:27], s[24:25], v[26:27]
	v_pk_add_f32 v[34:35], s[26:27], v[34:35]
	v_mov_b32_e32 v36, v26
	v_mov_b32_e32 v37, v34
	v_mov_b32_e32 v34, v27
	v_pk_add_f32 v[26:27], v[36:37], v[34:35]
	v_readfirstlane_b32 s24, v28
	v_pk_fma_f32 v[26:27], v[26:27], s[20:21], v[6:7] op_sel_hi:[1,1,0]
	v_readfirstlane_b32 s25, v29
	v_mul_f32_e32 v34, 0x4b800000, v27
	v_cmp_gt_f32_e32 vcc, s9, v27
	s_nop 1
	v_cndmask_b32_e32 v27, v27, v34, vcc
	v_rsq_f32_e32 v27, v27
	v_lshl_add_u64 v[34:35], s[10:11], 0, v[14:15]
	v_mul_f32_e32 v28, 0x45800000, v27
	v_cndmask_b32_e32 v28, v27, v28, vcc
	v_pk_mul_f32 v[2:3], v[2:3], v[28:29] op_sel_hi:[1,0]
	v_pk_mul_f32 v[4:5], v[4:5], v[28:29] op_sel_hi:[1,0]
	v_cmp_gt_f32_e32 vcc, s9, v26
	s_nop 0
	v_pk_mul_f32 v[2:3], v[30:31], v[2:3]
	v_pk_mul_f32 v[4:5], v[32:33], v[4:5]
	v_cvt_pk_bf16_f32 v2, v2, v3
	v_cvt_pk_bf16_f32 v3, v4, v5
	global_store_dwordx2 v[34:35], v[2:3], off sc1
	s_nop 1
	v_mov_b64_e32 v[2:3], v[204:205]
	v_mul_f32_e32 v4, 0x4b800000, v26
	v_cndmask_b32_e32 v4, v26, v4, vcc
	v_rsq_f32_e32 v4, v4
	v_lshl_add_u64 v[26:27], s[10:11], 0, v[10:11]
	v_mul_f32_e32 v5, 0x45800000, v4
	v_cndmask_b32_e32 v4, v4, v5, vcc
	v_pk_mul_f32 v[4:5], v[22:23], v[4:5] op_sel_hi:[1,0]
	s_andn2_b64 vcc, exec, s[22:23]
	s_nop 0
	v_pk_mul_f32 v[4:5], v[2:3], v[4:5]
	s_nop 0
	v_cvt_pk_bf16_f32 v2, v4, v5
	global_store_dword v[26:27], v2, off sc1
	s_cbranch_vccnz .LBB0_645
	ds_read_b64 v[2:3], v7 offset:408
	s_waitcnt lgkmcnt(0)
	v_readfirstlane_b32 s22, v2
	v_readfirstlane_b32 s23, v3
	s_nop 1
	v_lshl_add_u64 v[22:23], s[22:23], 0, v[14:15]
	v_add_co_u32_e32 v22, vcc, 0xf9ed8000, v22
	s_nop 1
	v_addc_co_u32_e32 v23, vcc, -1, v23, vcc
	global_store_dwordx2 v[22:23], v[4:5], off sc1
	s_and_saveexec_b64 s[22:23], s[2:3]
	s_cbranch_execz .LBB0_644
	v_readfirstlane_b32 s24, v2
	v_readfirstlane_b32 s25, v3
	s_nop 1
	v_lshl_add_u64 v[2:3], s[24:25], 0, v[12:13]
	global_store_dword v[2:3], v25, off sc1
	s_branch .LBB0_644

.LBB0_656:
	ds_read_b64 v[94:95], v3 offset:272
	s_cmpk_lt_i32 s4, 0x100
	s_cselect_b32 s2, s15, 0x7fffffc0
	s_and_b32 s20, s4, 3
	s_and_b32 s2, s2, s5
	s_lshl_b32 s3, s20, 2
	v_mov_b32_e32 v104, s3
	v_or_b32_e32 v102, s2, v1
	s_waitcnt lgkmcnt(0)
	v_readfirstlane_b32 s2, v94
	v_readfirstlane_b32 s3, v95
	s_nop 4
	global_load_dword v127, v104, s[2:3]
	global_load_dword v128, v104, s[2:3] offset:16
	v_ashrrev_i32_e32 v103, 31, v102
	v_lshlrev_b64 v[94:95], 13, v[102:103]
	s_lshl_b32 s8, s20, 8
	v_lshl_add_u64 v[94:95], s[6:7], 0, v[94:95]
	v_lshl_add_u64 v[102:103], v[94:95], 0, s[8:9]
	s_lshl_b32 s8, s20, 9
	v_lshlrev_b32_e32 v110, 2, v4
	v_mov_b32_e32 v111, v3
	v_lshl_add_u64 v[94:95], v[94:95], 0, s[8:9]
	v_lshl_add_u64 v[112:113], v[102:103], 0, v[2:3]
	v_lshl_add_u64 v[94:95], v[94:95], 0, v[110:111]
	global_load_dwordx4 v[102:105], v[112:113], off offset:2704
	global_load_dwordx4 v[106:109], v[112:113], off offset:2688
	s_nop 0
	global_load_dwordx4 v[110:113], v[94:95], off offset:3712
	global_load_dwordx4 v[114:117], v[94:95], off offset:3728
	global_load_dwordx4 v[118:121], v[94:95], off offset:3744
	global_load_dwordx4 v[122:125], v[94:95], off offset:3760
	v_add_u32_e32 v126, v97, v4
	v_lshl_add_u64 v[66:67], s[10:11], 0, v[64:65]
	v_lshl_add_u64 v[68:69], s[10:11], 0, v[6:7]
	v_lshl_add_u64 v[70:71], s[10:11], 0, v[62:63]
	v_lshl_add_u64 v[72:73], s[10:11], 0, v[60:61]
	v_lshl_add_u64 v[74:75], s[10:11], 0, v[58:59]
	v_lshl_add_u64 v[76:77], s[10:11], 0, v[56:57]
	v_lshl_add_u64 v[78:79], s[10:11], 0, v[54:55]
	v_lshl_add_u64 v[80:81], s[10:11], 0, v[52:53]
	v_lshl_add_u64 v[82:83], s[10:11], 0, v[50:51]
	v_lshl_add_u64 v[84:85], s[10:11], 0, v[48:49]
	v_lshl_add_u64 v[86:87], s[10:11], 0, v[46:47]
	v_lshl_add_u64 v[88:89], s[10:11], 0, v[44:45]
	v_lshl_add_u64 v[90:91], s[10:11], 0, v[42:43]
	v_lshl_add_u64 v[92:93], s[10:11], 0, v[40:41]
	v_lshl_add_u64 v[154:155], s[10:11], 0, v[38:39]
	v_lshl_add_u64 v[156:157], s[10:11], 0, v[36:37]
	v_lshl_add_u64 v[158:159], s[10:11], 0, v[34:35]
	v_lshl_add_u64 v[160:161], s[10:11], 0, v[30:31]
	v_lshl_add_u64 v[162:163], s[10:11], 0, v[28:29]
	v_lshl_add_u64 v[164:165], s[10:11], 0, v[26:27]
	v_lshl_add_u64 v[166:167], s[10:11], 0, v[24:25]
	v_lshl_add_u64 v[168:169], s[10:11], 0, v[22:23]
	v_lshl_add_u64 v[170:171], s[10:11], 0, v[20:21]
	v_lshl_add_u64 v[172:173], s[10:11], 0, v[18:19]
	v_lshl_add_u64 v[174:175], s[10:11], 0, v[16:17]
	v_lshl_add_u64 v[176:177], s[10:11], 0, v[14:15]
	v_lshl_add_u64 v[178:179], s[10:11], 0, v[12:13]
	v_lshl_add_u64 v[180:181], s[10:11], 0, v[10:11]
	s_waitcnt vmcnt(7)
	v_mul_f32_e32 v94, 0xbfb8aa3b, v127
	s_waitcnt vmcnt(6)
	v_mul_f32_e32 v95, 0xbfb8aa3b, v128
	v_exp_f32_e32 v94, v94
	v_exp_f32_e32 v95, v95
	v_add_f32_e32 v94, 1.0, v94
	v_add_f32_e32 v95, 1.0, v95
	v_rcp_f32_e32 v94, v94
	v_rcp_f32_e32 v95, v95
	s_waitcnt vmcnt(3)
	v_cvt_pk_bf16_f32 v110, v110, v111
	v_cmp_gt_f32_e32 vcc, s16, v94
	v_cvt_pk_bf16_f32 v111, v112, v113
	s_waitcnt vmcnt(2)
	v_cvt_pk_bf16_f32 v112, v114, v115
	v_cvt_pk_bf16_f32 v113, v116, v117
	v_cmp_gt_f32_e64 s[2:3], s16, v95
	s_and_b64 s[20:21], vcc, exec
	s_waitcnt vmcnt(1)
	v_cvt_pk_bf16_f32 v114, v118, v119
	v_cvt_pk_bf16_f32 v115, v120, v121
	s_waitcnt vmcnt(0)
	v_cvt_pk_bf16_f32 v116, v122, v123
	v_cvt_pk_bf16_f32 v117, v124, v125
	ds_write_b128 v98, v[110:113] offset:21504
	ds_write_b128 v98, v[114:117] offset:21520
	v_cndmask_b32_e64 v111, 0, v101, s[2:3]
	s_cselect_b32 s8, 32, 0
	s_and_b64 s[2:3], s[2:3], exec
	v_ldexp_f32 v94, v94, s8
	s_cselect_b32 s2, 32, 0
	v_log_f32_e32 v94, v94
	v_ldexp_f32 v95, v95, s2
	v_log_f32_e32 v95, v95
	v_cndmask_b32_e32 v110, 0, v101, vcc
	v_mul_f32_e32 v112, 0x3f317217, v94
	v_fma_f32 v112, v94, s17, -v112
	v_mul_f32_e32 v113, 0x3f317217, v95
	v_fmac_f32_e32 v112, 0x3377d1cf, v94
	v_fma_f32 v113, v95, s17, -v113
	v_fmac_f32_e32 v112, 0x3f317217, v94
	v_fmac_f32_e32 v113, 0x3377d1cf, v95
	v_cmp_lt_f32_e64 vcc, |v94|, s18
	v_fmac_f32_e32 v113, 0x3f317217, v95
	s_add_i32 s4, s4, s56
	v_cndmask_b32_e32 v94, v94, v112, vcc
	v_cmp_lt_f32_e64 vcc, |v95|, s18
	v_sub_f32_e32 v94, v94, v110
	v_mul_f32_e32 v94, v94, v5
	v_cndmask_b32_e32 v95, v95, v113, vcc
	v_sub_f32_e32 v95, v95, v111
	v_mul_f32_e32 v94, 0x3fb8aa3b, v94
	v_mul_f32_e32 v95, v95, v96
	v_exp_f32_e32 v94, v94
	v_mul_f32_e32 v95, 0x3fb8aa3b, v95
	v_exp_f32_e32 v95, v95
	v_add_co_u32_e32 v68, vcc, s19, v68
	v_mul_f32_e32 v94, 0x3e000000, v94
	v_mul_f32_e32 v114, 0x3e000000, v95
	v_pk_mul_f32 v[110:111], v[106:107], v[94:95] op_sel_hi:[1,0]
	v_pk_mul_f32 v[112:113], v[108:109], v[94:95] op_sel_hi:[1,0]
	v_pk_mul_f32 v[116:117], v[102:103], v[94:95] op_sel_hi:[1,0]
	v_pk_mul_f32 v[94:95], v[104:105], v[94:95] op_sel_hi:[1,0]
	v_cvt_pk_bf16_f32 v110, v110, v111
	v_cvt_pk_bf16_f32 v111, v112, v113
	v_cvt_pk_bf16_f32 v113, v94, v95
	v_pk_mul_f32 v[94:95], v[106:107], v[114:115] op_sel_hi:[1,0]
	v_pk_mul_f32 v[106:107], v[108:109], v[114:115] op_sel_hi:[1,0]
	v_pk_mul_f32 v[108:109], v[102:103], v[114:115] op_sel_hi:[1,0]
	v_pk_mul_f32 v[114:115], v[104:105], v[114:115] op_sel_hi:[1,0]
	v_cvt_pk_bf16_f32 v112, v116, v117
	v_cvt_pk_bf16_f32 v102, v94, v95
	v_cvt_pk_bf16_f32 v103, v106, v107
	v_cvt_pk_bf16_f32 v104, v108, v109
	v_cvt_pk_bf16_f32 v105, v114, v115
	ds_write_b128 v126, v[110:113] offset:1024
	ds_write_b128 v126, v[102:105] offset:11264
	s_waitcnt lgkmcnt(0)
	s_barrier
	ds_read_b64_tr_b16 v[102:103], v100 offset:1024
	ds_read_b64_tr_b16 v[104:105], v100 offset:1664
	ds_read_b64_tr_b16 v[106:107], v99 offset:21504
	ds_read_b64_tr_b16 v[108:109], v99 offset:22656
	ds_read_b64_tr_b16 v[110:111], v99 offset:30720
	ds_read_b64_tr_b16 v[112:113], v99 offset:31872
	ds_read_b64_tr_b16 v[116:117], v100 offset:1696
	ds_read_b64_tr_b16 v[114:115], v100 offset:1056
	ds_read_b64_tr_b16 v[118:119], v100 offset:1088
	ds_read_b64_tr_b16 v[122:123], v100 offset:1120
	ds_read_b64_tr_b16 v[120:121], v100 offset:1728
	ds_read_b64_tr_b16 v[124:125], v100 offset:1760
	ds_read_b64_tr_b16 v[126:127], v100 offset:11264
	ds_read_b64_tr_b16 v[128:129], v100 offset:11904
	ds_read_b64_tr_b16 v[132:133], v100 offset:11936
	ds_read_b64_tr_b16 v[130:131], v100 offset:11296
	ds_read_b64_tr_b16 v[134:135], v100 offset:11328
	ds_read_b64_tr_b16 v[138:139], v100 offset:11360
	ds_read_b64_tr_b16 v[136:137], v100 offset:11968
	ds_read_b64_tr_b16 v[140:141], v100 offset:12000
	ds_read_b64_tr_b16 v[142:143], v100 offset:6144
	ds_read_b64_tr_b16 v[144:145], v100 offset:6784
	s_waitcnt lgkmcnt(14)
	v_mfma_f32_16x16x32_bf16 v[102:105], v[102:105], v[106:109], 0
	ds_read_b64_tr_b16 v[148:149], v100 offset:6816
	ds_read_b64_tr_b16 v[146:147], v100 offset:6176
	ds_read_b64_tr_b16 v[150:151], v100 offset:6208
	v_lshl_add_u64 v[94:95], s[10:11], 0, v[32:33]
	v_addc_co_u32_e32 v69, vcc, 0, v69, vcc
	v_mfma_f32_16x16x32_bf16 v[114:117], v[114:117], v[106:109], 0
	s_waitcnt lgkmcnt(14)
	v_mfma_f32_16x16x32_bf16 v[118:121], v[118:121], v[106:109], 0
	s_waitcnt lgkmcnt(13)
	v_mfma_f32_16x16x32_bf16 v[122:125], v[122:125], v[106:109], 0
	s_waitcnt lgkmcnt(11)
	v_mfma_f32_16x16x32_bf16 v[126:129], v[126:129], v[106:109], 0
	s_waitcnt lgkmcnt(9)
	v_mfma_f32_16x16x32_bf16 v[130:133], v[130:133], v[106:109], 0
	s_waitcnt lgkmcnt(6)
	v_mfma_f32_16x16x32_bf16 v[134:137], v[134:137], v[106:109], 0
	s_waitcnt lgkmcnt(5)
	v_mfma_f32_16x16x32_bf16 v[106:109], v[138:141], v[106:109], 0
	ds_read_b64_tr_b16 v[138:139], v100 offset:6240
	ds_read_b64_tr_b16 v[152:153], v100 offset:6848
	ds_read_b64_tr_b16 v[140:141], v100 offset:6880
	s_waitcnt lgkmcnt(6)
	v_mfma_f32_16x16x32_bf16 v[102:105], v[142:145], v[110:113], v[102:105]
	ds_read_b64_tr_b16 v[142:143], v100 offset:16384
	ds_read_b64_tr_b16 v[144:145], v100 offset:17024
	s_waitcnt lgkmcnt(6)
	v_mfma_f32_16x16x32_bf16 v[114:117], v[146:149], v[110:113], v[114:117]
	s_waitcnt lgkmcnt(3)
	v_mfma_f32_16x16x32_bf16 v[118:121], v[150:153], v[110:113], v[118:121]
	ds_read_b64_tr_b16 v[148:149], v100 offset:17056
	ds_read_b64_tr_b16 v[146:147], v100 offset:16416
	ds_read_b64_tr_b16 v[150:151], v100 offset:16448
	s_waitcnt lgkmcnt(5)
	v_mfma_f32_16x16x32_bf16 v[122:125], v[138:141], v[110:113], v[122:125]
	ds_read_b64_tr_b16 v[138:139], v100 offset:16480
	ds_read_b64_tr_b16 v[152:153], v100 offset:17088
	ds_read_b64_tr_b16 v[140:141], v100 offset:17120
	s_waitcnt lgkmcnt(6)
	v_mfma_f32_16x16x32_bf16 v[126:129], v[142:145], v[110:113], v[126:129]
	v_lshl_add_u64 v[142:143], s[10:11], 0, v[8:9]
	s_add_u32 s10, s10, s12
	s_addc_u32 s11, s11, s13
	s_add_i32 s5, s5, s14
	s_cmpk_lt_i32 s4, 0x180
	s_waitcnt lgkmcnt(4)
	v_mfma_f32_16x16x32_bf16 v[130:133], v[146:149], v[110:113], v[130:133]
	s_waitcnt lgkmcnt(1)
	v_mfma_f32_16x16x32_bf16 v[134:137], v[150:153], v[110:113], v[134:137]
	s_waitcnt lgkmcnt(0)
	v_mfma_f32_16x16x32_bf16 v[106:109], v[138:141], v[110:113], v[106:109]
	global_store_dword v[66:67], v102, off sc1
	global_store_dword v[68:69], v103, off offset:512 sc1
	global_store_dword v[68:69], v104, off offset:1024 sc1
	global_store_dword v[68:69], v105, off offset:1536 sc1
	global_store_dword v[70:71], v114, off sc1
	global_store_dword v[72:73], v115, off sc1
	global_store_dword v[74:75], v116, off sc1
	global_store_dword v[76:77], v117, off sc1
	global_store_dword v[78:79], v118, off sc1
	global_store_dword v[80:81], v119, off sc1
	global_store_dword v[82:83], v120, off sc1
	global_store_dword v[84:85], v121, off sc1
	global_store_dword v[86:87], v122, off sc1
	global_store_dword v[88:89], v123, off sc1
	global_store_dword v[90:91], v124, off sc1
	global_store_dword v[92:93], v125, off sc1
	global_store_dword v[154:155], v126, off sc1
	global_store_dword v[156:157], v127, off sc1
	global_store_dword v[158:159], v128, off sc1
	global_store_dword v[94:95], v129, off sc1
	global_store_dword v[160:161], v130, off sc1
	global_store_dword v[162:163], v131, off sc1
	global_store_dword v[164:165], v132, off sc1
	global_store_dword v[166:167], v133, off sc1
	global_store_dword v[168:169], v134, off sc1
	global_store_dword v[170:171], v135, off sc1
	global_store_dword v[172:173], v136, off sc1
	global_store_dword v[174:175], v137, off sc1
	global_store_dword v[176:177], v106, off sc1
	global_store_dword v[178:179], v107, off sc1
	global_store_dword v[180:181], v108, off sc1
	global_store_dword v[142:143], v109, off sc1
	s_barrier
	s_cbranch_scc1 .LBB0_656

.LBB0_890:
	s_or_b64 exec, exec, s[10:11]
	s_add_i32 s14, s14, s18
	s_add_u32 s29, s29, s20
	s_addc_u32 s40, s40, s21
	s_waitcnt vmcnt(7)
	v_cvt_pk_bf16_f32 v16, v58, s0
	v_lshl_add_u64 v[8:9], v[8:9], 0, s[22:23]
	v_lshl_add_u64 v[10:11], v[10:11], 0, s[24:25]
	v_lshl_add_u64 v[12:13], v[12:13], 0, s[26:27]
	s_cmpk_lt_i32 s14, 0x1c00
	v_lshl_add_u64 v[14:15], v[14:15], 0, s[26:27]
	global_store_short v[38:39], v16, off offset:896 sc1
	s_cbranch_scc0 .LBB0_986

.LBB0_938:
	s_or_b64 exec, exec, s[10:11]
	v_cndmask_b32_e64 v30, 0, 1, s[36:37]
	v_cmp_ne_u32_e64 s[10:11], 1, v30
	s_andn2_b64 vcc, exec, s[36:37]
	v_lshl_add_u64 v[30:31], s[16:17], 0, v[8:9]
	s_cbranch_vccnz .LBB0_942
	v_mul_f32_e32 v66, v35, v35
	v_fmac_f32_e32 v66, v34, v34
	s_nop 1
	v_add_f32_dpp v66, v66, v66 quad_perm:[1,0,3,2] row_mask:0xf bank_mask:0xf bound_ctrl:1
	s_nop 1
	v_add_f32_dpp v66, v66, v66 quad_perm:[2,3,0,1] row_mask:0xf bank_mask:0xf bound_ctrl:1
	s_nop 1
	v_add_f32_dpp v66, v66, v66 row_half_mirror row_mask:0xf bank_mask:0xf bound_ctrl:1
	s_nop 1
	v_add_f32_dpp v66, v66, v66 row_mirror row_mask:0xf bank_mask:0xf bound_ctrl:1
	s_nop 0
	v_readlane_b32 s38, v66, 0
	v_readlane_b32 s12, v66, 16
	v_readlane_b32 s39, v66, 32
	v_readlane_b32 s19, v66, 48
	s_and_saveexec_b64 s[36:37], s[2:3]
	s_cbranch_execz .LBB0_941
	v_mov_b32_e32 v66, s12
	v_mov_b32_e32 v67, s19
	v_pk_add_f32 v[66:67], s[38:39], v[66:67]
	s_nop 0
	v_add_f32_e32 v66, v66, v67
	v_fmamk_f32 v66, v66, 0x3c2aaaab, v56
	v_mul_f32_e32 v67, 0x4b800000, v66
	v_cmp_gt_f32_e32 vcc, s15, v66
	s_nop 1
	v_cndmask_b32_e32 v66, v66, v67, vcc
	v_rsq_f32_e32 v66, v66
	s_nop 0
	v_mul_f32_e32 v67, 0x45800000, v66
	v_cndmask_b32_e32 v66, v66, v67, vcc
	v_mul_f32_e32 v35, v35, v66
	v_mul_f32_e32 v34, v34, v66
	s_waitcnt vmcnt(1)
	v_mul_f32_e32 v66, v27, v35
	v_mul_f32_e32 v34, v26, v34
	v_pk_mul_f32 v[66:67], v[16:17], v[66:67] op_sel:[1,0] op_sel_hi:[0,0]
	v_pk_fma_f32 v[68:69], v[16:17], v[34:35], v[66:67] neg_lo:[0,0,1] neg_hi:[0,0,1]
	v_pk_fma_f32 v[34:35], v[16:17], v[34:35], v[66:67] op_sel_hi:[1,0,1]
	s_nop 0
	v_mov_b32_e32 v69, v35
	v_pk_mul_f32 v[34:35], v[68:69], s[28:29] op_sel_hi:[1,0]
	s_nop 0
	v_cvt_pk_bf16_f32 v66, v34, v35
	v_add_co_u32_e32 v34, vcc, 0xabe8000, v30
	s_nop 1
	v_addc_co_u32_e32 v35, vcc, 0, v31, vcc
	global_store_dword v[34:35], v66, off sc1

.LBB0_942:
	s_waitcnt vmcnt(8)
	v_mul_f32_e32 v66, v39, v39
	v_fmac_f32_e32 v66, v38, v38
	v_mad_i64_i32 v[34:35], s[36:37], s34, v57, v[6:7]
	s_nop 0
	v_add_f32_dpp v66, v66, v66 quad_perm:[1,0,3,2] row_mask:0xf bank_mask:0xf bound_ctrl:1
	s_nop 1
	v_add_f32_dpp v66, v66, v66 quad_perm:[2,3,0,1] row_mask:0xf bank_mask:0xf bound_ctrl:1
	s_nop 1
	v_add_f32_dpp v66, v66, v66 row_half_mirror row_mask:0xf bank_mask:0xf bound_ctrl:1
	s_nop 1
	v_add_f32_dpp v66, v66, v66 row_mirror row_mask:0xf bank_mask:0xf bound_ctrl:1
	s_nop 0
	v_readlane_b32 s38, v66, 0
	v_readlane_b32 s12, v66, 16
	v_readlane_b32 s39, v66, 32
	v_readlane_b32 s19, v66, 48
	s_and_saveexec_b64 s[36:37], s[2:3]
	s_cbranch_execz .LBB0_944
	v_mov_b32_e32 v66, s12
	v_mov_b32_e32 v67, s19
	v_pk_add_f32 v[66:67], s[38:39], v[66:67]
	s_nop 0
	v_add_f32_e32 v66, v66, v67
	v_fmamk_f32 v66, v66, 0x3c2aaaab, v56
	v_mul_f32_e32 v67, 0x4b800000, v66
	v_cmp_gt_f32_e32 vcc, s15, v66
	s_nop 1
	v_cndmask_b32_e32 v66, v66, v67, vcc
	v_rsq_f32_e32 v66, v66
	s_nop 0
	v_mul_f32_e32 v67, 0x45800000, v66
	v_cndmask_b32_e32 v66, v66, v67, vcc
	v_mul_f32_e32 v39, v39, v66
	v_mul_f32_e32 v38, v38, v66
	s_waitcnt vmcnt(0)
	v_mul_f32_e32 v66, v23, v39
	v_mul_f32_e32 v38, v22, v38
	v_pk_mul_f32 v[66:67], v[16:17], v[66:67] op_sel:[1,0] op_sel_hi:[0,0]
	v_pk_fma_f32 v[68:69], v[16:17], v[38:39], v[66:67] neg_lo:[0,0,1] neg_hi:[0,0,1]
	v_pk_fma_f32 v[38:39], v[16:17], v[38:39], v[66:67] op_sel_hi:[1,0,1]
	s_nop 0
	v_cvt_pk_bf16_f32 v38, v68, v39
	global_store_dword v[34:35], v38, off sc1
.LBB0_944:
	s_or_b64 exec, exec, s[36:37]
	s_ashr_i32 s35, s34, 31
	s_lshl_b64 s[34:35], s[34:35], 10
	v_lshl_add_u64 v[38:39], v[4:5], 0, s[34:35]
	s_waitcnt vmcnt(7)
	v_cvt_pk_bf16_f32 v65, v65, s0
	s_and_b64 vcc, exec, s[10:11]
	global_store_short v[38:39], v65, off sc1
	s_cbranch_vccnz .LBB0_948
	v_mul_f32_e32 v65, v55, v55
	v_fmac_f32_e32 v65, v54, v54
	s_nop 1
	v_add_f32_dpp v65, v65, v65 quad_perm:[1,0,3,2] row_mask:0xf bank_mask:0xf bound_ctrl:1
	s_nop 1
	v_add_f32_dpp v65, v65, v65 quad_perm:[2,3,0,1] row_mask:0xf bank_mask:0xf bound_ctrl:1
	s_nop 1
	v_add_f32_dpp v65, v65, v65 row_half_mirror row_mask:0xf bank_mask:0xf bound_ctrl:1
	s_nop 1
	v_add_f32_dpp v65, v65, v65 row_mirror row_mask:0xf bank_mask:0xf bound_ctrl:1
	s_nop 0
	v_readlane_b32 s36, v65, 0
	v_readlane_b32 s12, v65, 16
	v_readlane_b32 s37, v65, 32
	v_readlane_b32 s19, v65, 48
	s_and_saveexec_b64 s[34:35], s[2:3]
	s_cbranch_execz .LBB0_947
	v_mov_b32_e32 v66, s12
	v_mov_b32_e32 v67, s19
	v_pk_add_f32 v[66:67], s[36:37], v[66:67]
	s_nop 0
	v_add_f32_e32 v65, v66, v67
	v_fmamk_f32 v65, v65, 0x3c2aaaab, v56
	v_mul_f32_e32 v66, 0x4b800000, v65
	v_cmp_gt_f32_e32 vcc, s15, v65
	s_nop 1
	v_cndmask_b32_e32 v65, v65, v66, vcc
	v_rsq_f32_e32 v65, v65
	s_nop 0
	v_mul_f32_e32 v66, 0x45800000, v65
	v_cndmask_b32_e32 v65, v65, v66, vcc
	v_mul_f32_e32 v55, v55, v65
	v_mul_f32_e32 v54, v54, v65
	s_waitcnt vmcnt(2)
	v_mul_f32_e32 v66, v27, v55
	v_mul_f32_e32 v54, v26, v54
	v_pk_mul_f32 v[66:67], v[16:17], v[66:67] op_sel:[1,0] op_sel_hi:[0,0]
	v_pk_fma_f32 v[68:69], v[16:17], v[54:55], v[66:67] neg_lo:[0,0,1] neg_hi:[0,0,1]
	v_pk_fma_f32 v[54:55], v[16:17], v[54:55], v[66:67] op_sel_hi:[1,0,1]
	s_nop 0
	v_mov_b32_e32 v69, v55
	v_pk_mul_f32 v[54:55], v[68:69], s[28:29] op_sel_hi:[1,0]
	s_nop 0
	v_cvt_pk_bf16_f32 v65, v54, v55
	v_add_co_u32_e32 v54, vcc, 0xabe8000, v30
	s_nop 1
	v_addc_co_u32_e32 v55, vcc, 0, v31, vcc
	global_store_dword v[54:55], v65, off offset:192 sc1

.LBB0_948:
	v_mul_f32_e32 v54, v53, v53
	v_fmac_f32_e32 v54, v52, v52
	s_nop 1
	v_add_f32_dpp v54, v54, v54 quad_perm:[1,0,3,2] row_mask:0xf bank_mask:0xf bound_ctrl:1
	s_nop 1
	v_add_f32_dpp v54, v54, v54 quad_perm:[2,3,0,1] row_mask:0xf bank_mask:0xf bound_ctrl:1
	s_nop 1
	v_add_f32_dpp v54, v54, v54 row_half_mirror row_mask:0xf bank_mask:0xf bound_ctrl:1
	s_nop 1
	v_add_f32_dpp v54, v54, v54 row_mirror row_mask:0xf bank_mask:0xf bound_ctrl:1
	s_nop 0
	v_readlane_b32 s36, v54, 0
	v_readlane_b32 s12, v54, 16
	v_readlane_b32 s37, v54, 32
	v_readlane_b32 s19, v54, 48
	s_and_saveexec_b64 s[34:35], s[2:3]
	s_cbranch_execz .LBB0_950
	v_mov_b32_e32 v54, s12
	v_mov_b32_e32 v55, s19
	v_pk_add_f32 v[54:55], s[36:37], v[54:55]
	s_nop 0
	v_add_f32_e32 v54, v54, v55
	v_fmamk_f32 v54, v54, 0x3c2aaaab, v56
	v_mul_f32_e32 v55, 0x4b800000, v54
	v_cmp_gt_f32_e32 vcc, s15, v54
	s_nop 1
	v_cndmask_b32_e32 v54, v54, v55, vcc
	v_rsq_f32_e32 v54, v54
	s_nop 0
	v_mul_f32_e32 v55, 0x45800000, v54
	v_cndmask_b32_e32 v54, v54, v55, vcc
	v_mul_f32_e32 v53, v53, v54
	v_mul_f32_e32 v52, v52, v54
	s_waitcnt vmcnt(1)
	v_mul_f32_e32 v54, v23, v53
	v_mul_f32_e32 v52, v22, v52
	v_pk_mul_f32 v[54:55], v[16:17], v[54:55] op_sel:[1,0] op_sel_hi:[0,0]
	v_pk_fma_f32 v[66:67], v[16:17], v[52:53], v[54:55] neg_lo:[0,0,1] neg_hi:[0,0,1]
	v_pk_fma_f32 v[52:53], v[16:17], v[52:53], v[54:55] op_sel_hi:[1,0,1]
	s_nop 0
	v_cvt_pk_bf16_f32 v52, v66, v53
	global_store_dword v[34:35], v52, off offset:192 sc1
.LBB0_950:
	s_or_b64 exec, exec, s[34:35]
	s_waitcnt vmcnt(7)
	v_cvt_pk_bf16_f32 v52, v64, s0
	s_and_b64 vcc, exec, s[10:11]
	global_store_short v[38:39], v52, off offset:128 sc1
	s_cbranch_vccnz .LBB0_954
	v_mul_f32_e32 v52, v51, v51
	v_fmac_f32_e32 v52, v50, v50
	s_nop 1
	v_add_f32_dpp v52, v52, v52 quad_perm:[1,0,3,2] row_mask:0xf bank_mask:0xf bound_ctrl:1
	s_nop 1
	v_add_f32_dpp v52, v52, v52 quad_perm:[2,3,0,1] row_mask:0xf bank_mask:0xf bound_ctrl:1
	s_nop 1
	v_add_f32_dpp v52, v52, v52 row_half_mirror row_mask:0xf bank_mask:0xf bound_ctrl:1
	s_nop 1
	v_add_f32_dpp v52, v52, v52 row_mirror row_mask:0xf bank_mask:0xf bound_ctrl:1
	s_nop 0
	v_readlane_b32 s36, v52, 0
	v_readlane_b32 s12, v52, 16
	v_readlane_b32 s37, v52, 32
	v_readlane_b32 s19, v52, 48
	s_and_saveexec_b64 s[34:35], s[2:3]
	s_cbranch_execz .LBB0_953
	v_mov_b32_e32 v52, s12
	v_mov_b32_e32 v53, s19
	v_pk_add_f32 v[52:53], s[36:37], v[52:53]
	s_nop 0
	v_add_f32_e32 v52, v52, v53
	v_fmamk_f32 v52, v52, 0x3c2aaaab, v56
	v_mul_f32_e32 v53, 0x4b800000, v52
	v_cmp_gt_f32_e32 vcc, s15, v52
	s_nop 1
	v_cndmask_b32_e32 v52, v52, v53, vcc
	v_rsq_f32_e32 v52, v52
	s_nop 0
	v_mul_f32_e32 v53, 0x45800000, v52
	v_cndmask_b32_e32 v52, v52, v53, vcc
	v_mul_f32_e32 v51, v51, v52
	v_mul_f32_e32 v50, v50, v52
	s_waitcnt vmcnt(3)
	v_mul_f32_e32 v52, v27, v51
	v_mul_f32_e32 v50, v26, v50
	v_pk_mul_f32 v[52:53], v[16:17], v[52:53] op_sel:[1,0] op_sel_hi:[0,0]
	v_pk_fma_f32 v[54:55], v[16:17], v[50:51], v[52:53] neg_lo:[0,0,1] neg_hi:[0,0,1]
	v_pk_fma_f32 v[50:51], v[16:17], v[50:51], v[52:53] op_sel_hi:[1,0,1]
	s_nop 0
	v_mov_b32_e32 v55, v51
	v_pk_mul_f32 v[50:51], v[54:55], s[28:29] op_sel_hi:[1,0]
	s_nop 0
	v_cvt_pk_bf16_f32 v52, v50, v51
	v_add_co_u32_e32 v50, vcc, 0xabe8000, v30
	s_nop 1
	v_addc_co_u32_e32 v51, vcc, 0, v31, vcc
	global_store_dword v[50:51], v52, off offset:384 sc1

.LBB0_954:
	v_mul_f32_e32 v50, v49, v49
	v_fmac_f32_e32 v50, v48, v48
	s_nop 1
	v_add_f32_dpp v50, v50, v50 quad_perm:[1,0,3,2] row_mask:0xf bank_mask:0xf bound_ctrl:1
	s_nop 1
	v_add_f32_dpp v50, v50, v50 quad_perm:[2,3,0,1] row_mask:0xf bank_mask:0xf bound_ctrl:1
	s_nop 1
	v_add_f32_dpp v50, v50, v50 row_half_mirror row_mask:0xf bank_mask:0xf bound_ctrl:1
	s_nop 1
	v_add_f32_dpp v50, v50, v50 row_mirror row_mask:0xf bank_mask:0xf bound_ctrl:1
	s_nop 0
	v_readlane_b32 s36, v50, 0
	v_readlane_b32 s12, v50, 16
	v_readlane_b32 s37, v50, 32
	v_readlane_b32 s19, v50, 48
	s_and_saveexec_b64 s[34:35], s[2:3]
	s_cbranch_execz .LBB0_956
	v_mov_b32_e32 v50, s12
	v_mov_b32_e32 v51, s19
	v_pk_add_f32 v[50:51], s[36:37], v[50:51]
	s_nop 0
	v_add_f32_e32 v50, v50, v51
	v_fmamk_f32 v50, v50, 0x3c2aaaab, v56
	v_mul_f32_e32 v51, 0x4b800000, v50
	v_cmp_gt_f32_e32 vcc, s15, v50
	s_nop 1
	v_cndmask_b32_e32 v50, v50, v51, vcc
	v_rsq_f32_e32 v50, v50
	s_nop 0
	v_mul_f32_e32 v51, 0x45800000, v50
	v_cndmask_b32_e32 v50, v50, v51, vcc
	v_mul_f32_e32 v49, v49, v50
	v_mul_f32_e32 v48, v48, v50
	s_waitcnt vmcnt(2)
	v_mul_f32_e32 v50, v23, v49
	v_mul_f32_e32 v48, v22, v48
	v_pk_mul_f32 v[50:51], v[16:17], v[50:51] op_sel:[1,0] op_sel_hi:[0,0]
	v_pk_fma_f32 v[52:53], v[16:17], v[48:49], v[50:51] neg_lo:[0,0,1] neg_hi:[0,0,1]
	v_pk_fma_f32 v[48:49], v[16:17], v[48:49], v[50:51] op_sel_hi:[1,0,1]
	s_nop 0
	v_cvt_pk_bf16_f32 v48, v52, v49
	global_store_dword v[34:35], v48, off offset:384 sc1
.LBB0_956:
	s_or_b64 exec, exec, s[34:35]
	s_waitcnt vmcnt(7)
	v_cvt_pk_bf16_f32 v48, v63, s0
	s_and_b64 vcc, exec, s[10:11]
	global_store_short v[38:39], v48, off offset:256 sc1
	s_cbranch_vccnz .LBB0_960
	v_mul_f32_e32 v48, v47, v47
	v_fmac_f32_e32 v48, v46, v46
	s_nop 1
	v_add_f32_dpp v48, v48, v48 quad_perm:[1,0,3,2] row_mask:0xf bank_mask:0xf bound_ctrl:1
	s_nop 1
	v_add_f32_dpp v48, v48, v48 quad_perm:[2,3,0,1] row_mask:0xf bank_mask:0xf bound_ctrl:1
	s_nop 1
	v_add_f32_dpp v48, v48, v48 row_half_mirror row_mask:0xf bank_mask:0xf bound_ctrl:1
	s_nop 1
	v_add_f32_dpp v48, v48, v48 row_mirror row_mask:0xf bank_mask:0xf bound_ctrl:1
	s_nop 0
	v_readlane_b32 s36, v48, 0
	v_readlane_b32 s12, v48, 16
	v_readlane_b32 s37, v48, 32
	v_readlane_b32 s19, v48, 48
	s_and_saveexec_b64 s[34:35], s[2:3]
	s_cbranch_execz .LBB0_959
	v_mov_b32_e32 v48, s12
	v_mov_b32_e32 v49, s19
	v_pk_add_f32 v[48:49], s[36:37], v[48:49]
	s_nop 0
	v_add_f32_e32 v48, v48, v49
	v_fmamk_f32 v48, v48, 0x3c2aaaab, v56
	v_mul_f32_e32 v49, 0x4b800000, v48
	v_cmp_gt_f32_e32 vcc, s15, v48
	s_nop 1
	v_cndmask_b32_e32 v48, v48, v49, vcc
	v_rsq_f32_e32 v48, v48
	s_nop 0
	v_mul_f32_e32 v49, 0x45800000, v48
	v_cndmask_b32_e32 v48, v48, v49, vcc
	v_mul_f32_e32 v47, v47, v48
	v_mul_f32_e32 v46, v46, v48
	s_waitcnt vmcnt(4)
	v_mul_f32_e32 v48, v27, v47
	v_mul_f32_e32 v46, v26, v46
	v_pk_mul_f32 v[48:49], v[16:17], v[48:49] op_sel:[1,0] op_sel_hi:[0,0]
	v_pk_fma_f32 v[50:51], v[16:17], v[46:47], v[48:49] neg_lo:[0,0,1] neg_hi:[0,0,1]
	v_pk_fma_f32 v[46:47], v[16:17], v[46:47], v[48:49] op_sel_hi:[1,0,1]
	s_nop 0
	v_mov_b32_e32 v51, v47
	v_pk_mul_f32 v[46:47], v[50:51], s[28:29] op_sel_hi:[1,0]
	s_nop 0
	v_cvt_pk_bf16_f32 v48, v46, v47
	v_add_co_u32_e32 v46, vcc, 0xabe8000, v30
	s_nop 1
	v_addc_co_u32_e32 v47, vcc, 0, v31, vcc
	global_store_dword v[46:47], v48, off offset:576 sc1

.LBB0_960:
	v_mul_f32_e32 v46, v45, v45
	v_fmac_f32_e32 v46, v44, v44
	s_nop 1
	v_add_f32_dpp v46, v46, v46 quad_perm:[1,0,3,2] row_mask:0xf bank_mask:0xf bound_ctrl:1
	s_nop 1
	v_add_f32_dpp v46, v46, v46 quad_perm:[2,3,0,1] row_mask:0xf bank_mask:0xf bound_ctrl:1
	s_nop 1
	v_add_f32_dpp v46, v46, v46 row_half_mirror row_mask:0xf bank_mask:0xf bound_ctrl:1
	s_nop 1
	v_add_f32_dpp v46, v46, v46 row_mirror row_mask:0xf bank_mask:0xf bound_ctrl:1
	s_nop 0
	v_readlane_b32 s36, v46, 0
	v_readlane_b32 s12, v46, 16
	v_readlane_b32 s37, v46, 32
	v_readlane_b32 s19, v46, 48
	s_and_saveexec_b64 s[34:35], s[2:3]
	s_cbranch_execz .LBB0_962
	v_mov_b32_e32 v46, s12
	v_mov_b32_e32 v47, s19
	v_pk_add_f32 v[46:47], s[36:37], v[46:47]
	s_nop 0
	v_add_f32_e32 v46, v46, v47
	v_fmamk_f32 v46, v46, 0x3c2aaaab, v56
	v_mul_f32_e32 v47, 0x4b800000, v46
	v_cmp_gt_f32_e32 vcc, s15, v46
	s_nop 1
	v_cndmask_b32_e32 v46, v46, v47, vcc
	v_rsq_f32_e32 v46, v46
	s_nop 0
	v_mul_f32_e32 v47, 0x45800000, v46
	v_cndmask_b32_e32 v46, v46, v47, vcc
	v_mul_f32_e32 v45, v45, v46
	v_mul_f32_e32 v44, v44, v46
	s_waitcnt vmcnt(3)
	v_mul_f32_e32 v46, v23, v45
	v_mul_f32_e32 v44, v22, v44
	v_pk_mul_f32 v[46:47], v[16:17], v[46:47] op_sel:[1,0] op_sel_hi:[0,0]
	v_pk_fma_f32 v[48:49], v[16:17], v[44:45], v[46:47] neg_lo:[0,0,1] neg_hi:[0,0,1]
	v_pk_fma_f32 v[44:45], v[16:17], v[44:45], v[46:47] op_sel_hi:[1,0,1]
	s_nop 0
	v_cvt_pk_bf16_f32 v44, v48, v45
	global_store_dword v[34:35], v44, off offset:576 sc1
.LBB0_962:
	s_or_b64 exec, exec, s[34:35]
	s_waitcnt vmcnt(7)
	v_cvt_pk_bf16_f32 v44, v62, s0
	s_and_b64 vcc, exec, s[10:11]
	global_store_short v[38:39], v44, off offset:384 sc1
	s_cbranch_vccnz .LBB0_966
	v_mul_f32_e32 v44, v43, v43
	v_fmac_f32_e32 v44, v42, v42
	s_nop 1
	v_add_f32_dpp v44, v44, v44 quad_perm:[1,0,3,2] row_mask:0xf bank_mask:0xf bound_ctrl:1
	s_nop 1
	v_add_f32_dpp v44, v44, v44 quad_perm:[2,3,0,1] row_mask:0xf bank_mask:0xf bound_ctrl:1
	s_nop 1
	v_add_f32_dpp v44, v44, v44 row_half_mirror row_mask:0xf bank_mask:0xf bound_ctrl:1
	s_nop 1
	v_add_f32_dpp v44, v44, v44 row_mirror row_mask:0xf bank_mask:0xf bound_ctrl:1
	s_nop 0
	v_readlane_b32 s36, v44, 0
	v_readlane_b32 s12, v44, 16
	v_readlane_b32 s37, v44, 32
	v_readlane_b32 s19, v44, 48
	s_and_saveexec_b64 s[34:35], s[2:3]
	s_cbranch_execz .LBB0_965
	v_mov_b32_e32 v44, s12
	v_mov_b32_e32 v45, s19
	v_pk_add_f32 v[44:45], s[36:37], v[44:45]
	s_nop 0
	v_add_f32_e32 v44, v44, v45
	v_fmamk_f32 v44, v44, 0x3c2aaaab, v56
	v_mul_f32_e32 v45, 0x4b800000, v44
	v_cmp_gt_f32_e32 vcc, s15, v44
	s_nop 1
	v_cndmask_b32_e32 v44, v44, v45, vcc
	v_rsq_f32_e32 v44, v44
	s_nop 0
	v_mul_f32_e32 v45, 0x45800000, v44
	v_cndmask_b32_e32 v44, v44, v45, vcc
	v_mul_f32_e32 v43, v43, v44
	v_mul_f32_e32 v42, v42, v44
	s_waitcnt vmcnt(5)
	v_mul_f32_e32 v44, v27, v43
	v_mul_f32_e32 v42, v26, v42
	v_pk_mul_f32 v[44:45], v[16:17], v[44:45] op_sel:[1,0] op_sel_hi:[0,0]
	v_pk_fma_f32 v[46:47], v[16:17], v[42:43], v[44:45] neg_lo:[0,0,1] neg_hi:[0,0,1]
	v_pk_fma_f32 v[42:43], v[16:17], v[42:43], v[44:45] op_sel_hi:[1,0,1]
	s_nop 0
	v_mov_b32_e32 v47, v43
	v_pk_mul_f32 v[42:43], v[46:47], s[28:29] op_sel_hi:[1,0]
	s_nop 0
	v_cvt_pk_bf16_f32 v44, v42, v43
	v_add_co_u32_e32 v42, vcc, 0xabe8000, v30
	s_nop 1
	v_addc_co_u32_e32 v43, vcc, 0, v31, vcc
	global_store_dword v[42:43], v44, off offset:768 sc1

.LBB0_966:
	v_mul_f32_e32 v42, v41, v41
	v_fmac_f32_e32 v42, v40, v40
	s_nop 1
	v_add_f32_dpp v42, v42, v42 quad_perm:[1,0,3,2] row_mask:0xf bank_mask:0xf bound_ctrl:1
	s_nop 1
	v_add_f32_dpp v42, v42, v42 quad_perm:[2,3,0,1] row_mask:0xf bank_mask:0xf bound_ctrl:1
	s_nop 1
	v_add_f32_dpp v42, v42, v42 row_half_mirror row_mask:0xf bank_mask:0xf bound_ctrl:1
	s_nop 1
	v_add_f32_dpp v42, v42, v42 row_mirror row_mask:0xf bank_mask:0xf bound_ctrl:1
	s_nop 0
	v_readlane_b32 s36, v42, 0
	v_readlane_b32 s12, v42, 16
	v_readlane_b32 s37, v42, 32
	v_readlane_b32 s19, v42, 48
	s_and_saveexec_b64 s[34:35], s[2:3]
	s_cbranch_execz .LBB0_968
	v_mov_b32_e32 v42, s12
	v_mov_b32_e32 v43, s19
	v_pk_add_f32 v[42:43], s[36:37], v[42:43]
	s_nop 0
	v_add_f32_e32 v42, v42, v43
	v_fmamk_f32 v42, v42, 0x3c2aaaab, v56
	v_mul_f32_e32 v43, 0x4b800000, v42
	v_cmp_gt_f32_e32 vcc, s15, v42
	s_nop 1
	v_cndmask_b32_e32 v42, v42, v43, vcc
	v_rsq_f32_e32 v42, v42
	s_nop 0
	v_mul_f32_e32 v43, 0x45800000, v42
	v_cndmask_b32_e32 v42, v42, v43, vcc
	v_mul_f32_e32 v41, v41, v42
	v_mul_f32_e32 v40, v40, v42
	s_waitcnt vmcnt(4)
	v_mul_f32_e32 v42, v23, v41
	v_mul_f32_e32 v40, v22, v40
	v_pk_mul_f32 v[42:43], v[16:17], v[42:43] op_sel:[1,0] op_sel_hi:[0,0]
	v_pk_fma_f32 v[44:45], v[16:17], v[40:41], v[42:43] neg_lo:[0,0,1] neg_hi:[0,0,1]
	v_pk_fma_f32 v[40:41], v[16:17], v[40:41], v[42:43] op_sel_hi:[1,0,1]
	s_nop 0
	v_cvt_pk_bf16_f32 v40, v44, v41
	global_store_dword v[34:35], v40, off offset:768 sc1
.LBB0_968:
	s_or_b64 exec, exec, s[34:35]
	s_waitcnt vmcnt(7)
	v_cvt_pk_bf16_f32 v40, v61, s0
	s_and_b64 vcc, exec, s[10:11]
	global_store_short v[38:39], v40, off offset:512 sc1
	s_cbranch_vccnz .LBB0_972
	v_mul_f32_e32 v40, v37, v37
	v_fmac_f32_e32 v40, v36, v36
	s_nop 1
	v_add_f32_dpp v40, v40, v40 quad_perm:[1,0,3,2] row_mask:0xf bank_mask:0xf bound_ctrl:1
	s_nop 1
	v_add_f32_dpp v40, v40, v40 quad_perm:[2,3,0,1] row_mask:0xf bank_mask:0xf bound_ctrl:1
	s_nop 1
	v_add_f32_dpp v40, v40, v40 row_half_mirror row_mask:0xf bank_mask:0xf bound_ctrl:1
	s_nop 1
	v_add_f32_dpp v40, v40, v40 row_mirror row_mask:0xf bank_mask:0xf bound_ctrl:1
	s_nop 0
	v_readlane_b32 s36, v40, 0
	v_readlane_b32 s12, v40, 16
	v_readlane_b32 s37, v40, 32
	v_readlane_b32 s19, v40, 48
	s_and_saveexec_b64 s[34:35], s[2:3]
	s_cbranch_execz .LBB0_971
	v_mov_b32_e32 v40, s12
	v_mov_b32_e32 v41, s19
	v_pk_add_f32 v[40:41], s[36:37], v[40:41]
	s_nop 0
	v_add_f32_e32 v40, v40, v41
	v_fmamk_f32 v40, v40, 0x3c2aaaab, v56
	v_mul_f32_e32 v41, 0x4b800000, v40
	v_cmp_gt_f32_e32 vcc, s15, v40
	s_nop 1
	v_cndmask_b32_e32 v40, v40, v41, vcc
	v_rsq_f32_e32 v40, v40
	s_nop 0
	v_mul_f32_e32 v41, 0x45800000, v40
	v_cndmask_b32_e32 v40, v40, v41, vcc
	v_mul_f32_e32 v37, v37, v40
	v_mul_f32_e32 v36, v36, v40
	s_waitcnt vmcnt(6)
	v_mul_f32_e32 v40, v27, v37
	v_mul_f32_e32 v36, v26, v36
	v_pk_mul_f32 v[40:41], v[16:17], v[40:41] op_sel:[1,0] op_sel_hi:[0,0]
	v_pk_fma_f32 v[42:43], v[16:17], v[36:37], v[40:41] neg_lo:[0,0,1] neg_hi:[0,0,1]
	v_pk_fma_f32 v[36:37], v[16:17], v[36:37], v[40:41] op_sel_hi:[1,0,1]
	s_nop 0
	v_mov_b32_e32 v43, v37
	v_pk_mul_f32 v[36:37], v[42:43], s[28:29] op_sel_hi:[1,0]
	s_nop 0
	v_cvt_pk_bf16_f32 v40, v36, v37
	v_add_co_u32_e32 v36, vcc, 0xabe8000, v30
	s_nop 1
	v_addc_co_u32_e32 v37, vcc, 0, v31, vcc
	global_store_dword v[36:37], v40, off offset:960 sc1

.LBB0_972:
	v_mul_f32_e32 v36, v33, v33
	v_fmac_f32_e32 v36, v32, v32
	s_nop 1
	v_add_f32_dpp v36, v36, v36 quad_perm:[1,0,3,2] row_mask:0xf bank_mask:0xf bound_ctrl:1
	s_nop 1
	v_add_f32_dpp v36, v36, v36 quad_perm:[2,3,0,1] row_mask:0xf bank_mask:0xf bound_ctrl:1
	s_nop 1
	v_add_f32_dpp v36, v36, v36 row_half_mirror row_mask:0xf bank_mask:0xf bound_ctrl:1
	s_nop 1
	v_add_f32_dpp v36, v36, v36 row_mirror row_mask:0xf bank_mask:0xf bound_ctrl:1
	s_nop 0
	v_readlane_b32 s36, v36, 0
	v_readlane_b32 s12, v36, 16
	v_readlane_b32 s37, v36, 32
	v_readlane_b32 s19, v36, 48
	s_and_saveexec_b64 s[34:35], s[2:3]
	s_cbranch_execz .LBB0_974
	v_mov_b32_e32 v36, s12
	v_mov_b32_e32 v37, s19
	v_pk_add_f32 v[36:37], s[36:37], v[36:37]
	s_nop 0
	v_add_f32_e32 v36, v36, v37
	v_fmamk_f32 v36, v36, 0x3c2aaaab, v56
	v_mul_f32_e32 v37, 0x4b800000, v36
	v_cmp_gt_f32_e32 vcc, s15, v36
	s_nop 1
	v_cndmask_b32_e32 v36, v36, v37, vcc
	v_rsq_f32_e32 v36, v36
	s_nop 0
	v_mul_f32_e32 v37, 0x45800000, v36
	v_cndmask_b32_e32 v36, v36, v37, vcc
	v_mul_f32_e32 v33, v33, v36
	v_mul_f32_e32 v32, v32, v36
	s_waitcnt vmcnt(5)
	v_mul_f32_e32 v36, v23, v33
	v_mul_f32_e32 v32, v22, v32
	v_pk_mul_f32 v[36:37], v[16:17], v[36:37] op_sel:[1,0] op_sel_hi:[0,0]
	v_pk_fma_f32 v[40:41], v[16:17], v[32:33], v[36:37] neg_lo:[0,0,1] neg_hi:[0,0,1]
	v_pk_fma_f32 v[32:33], v[16:17], v[32:33], v[36:37] op_sel_hi:[1,0,1]
	s_nop 0
	v_cvt_pk_bf16_f32 v32, v40, v33
	global_store_dword v[34:35], v32, off offset:960 sc1
.LBB0_974:
	s_or_b64 exec, exec, s[34:35]
	s_waitcnt vmcnt(7)
	v_cvt_pk_bf16_f32 v32, v60, s0
	s_and_b64 vcc, exec, s[10:11]
	global_store_short v[38:39], v32, off offset:640 sc1
	s_cbranch_vccnz .LBB0_978
	v_mul_f32_e32 v32, v29, v29
	v_fmac_f32_e32 v32, v28, v28
	s_nop 1
	v_add_f32_dpp v32, v32, v32 quad_perm:[1,0,3,2] row_mask:0xf bank_mask:0xf bound_ctrl:1
	s_nop 1
	v_add_f32_dpp v32, v32, v32 quad_perm:[2,3,0,1] row_mask:0xf bank_mask:0xf bound_ctrl:1
	s_nop 1
	v_add_f32_dpp v32, v32, v32 row_half_mirror row_mask:0xf bank_mask:0xf bound_ctrl:1
	s_nop 1
	v_add_f32_dpp v32, v32, v32 row_mirror row_mask:0xf bank_mask:0xf bound_ctrl:1
	s_nop 0
	v_readlane_b32 s36, v32, 0
	v_readlane_b32 s12, v32, 16
	v_readlane_b32 s37, v32, 32
	v_readlane_b32 s19, v32, 48
	s_and_saveexec_b64 s[34:35], s[2:3]
	s_cbranch_execz .LBB0_977
	v_mov_b32_e32 v32, s12
	v_mov_b32_e32 v33, s19
	v_pk_add_f32 v[32:33], s[36:37], v[32:33]
	s_nop 0
	v_add_f32_e32 v32, v32, v33
	v_fmamk_f32 v32, v32, 0x3c2aaaab, v56
	v_mul_f32_e32 v33, 0x4b800000, v32
	v_cmp_gt_f32_e32 vcc, s15, v32
	s_nop 1
	v_cndmask_b32_e32 v32, v32, v33, vcc
	v_rsq_f32_e32 v32, v32
	s_nop 0
	v_mul_f32_e32 v33, 0x45800000, v32
	v_cndmask_b32_e32 v32, v32, v33, vcc
	v_mul_f32_e32 v29, v29, v32
	v_mul_f32_e32 v28, v28, v32
	s_waitcnt vmcnt(7)
	v_mul_f32_e32 v32, v27, v29
	v_mul_f32_e32 v28, v26, v28
	v_pk_mul_f32 v[32:33], v[16:17], v[32:33] op_sel:[1,0] op_sel_hi:[0,0]
	v_pk_fma_f32 v[36:37], v[16:17], v[28:29], v[32:33] neg_lo:[0,0,1] neg_hi:[0,0,1]
	v_pk_fma_f32 v[28:29], v[16:17], v[28:29], v[32:33] op_sel_hi:[1,0,1]
	s_nop 0
	v_mov_b32_e32 v37, v29
	v_pk_mul_f32 v[28:29], v[36:37], s[28:29] op_sel_hi:[1,0]
	s_nop 0
	v_cvt_pk_bf16_f32 v32, v28, v29
	v_add_co_u32_e32 v28, vcc, 0xabe8000, v30
	s_nop 1
	v_addc_co_u32_e32 v29, vcc, 0, v31, vcc
	global_store_dword v[28:29], v32, off offset:1152 sc1

.LBB0_978:
	v_mul_f32_e32 v28, v25, v25
	v_fmac_f32_e32 v28, v24, v24
	s_nop 1
	v_add_f32_dpp v28, v28, v28 quad_perm:[1,0,3,2] row_mask:0xf bank_mask:0xf bound_ctrl:1
	s_nop 1
	v_add_f32_dpp v28, v28, v28 quad_perm:[2,3,0,1] row_mask:0xf bank_mask:0xf bound_ctrl:1
	s_nop 1
	v_add_f32_dpp v28, v28, v28 row_half_mirror row_mask:0xf bank_mask:0xf bound_ctrl:1
	s_nop 1
	v_add_f32_dpp v28, v28, v28 row_mirror row_mask:0xf bank_mask:0xf bound_ctrl:1
	s_nop 0
	v_readlane_b32 s36, v28, 0
	v_readlane_b32 s12, v28, 16
	v_readlane_b32 s37, v28, 32
	v_readlane_b32 s19, v28, 48
	s_and_saveexec_b64 s[34:35], s[2:3]
	s_cbranch_execz .LBB0_980
	v_mov_b32_e32 v28, s12
	v_mov_b32_e32 v29, s19
	v_pk_add_f32 v[28:29], s[36:37], v[28:29]
	s_nop 0
	v_add_f32_e32 v28, v28, v29
	v_fmamk_f32 v28, v28, 0x3c2aaaab, v56
	v_mul_f32_e32 v29, 0x4b800000, v28
	v_cmp_gt_f32_e32 vcc, s15, v28
	s_nop 1
	v_cndmask_b32_e32 v28, v28, v29, vcc
	v_rsq_f32_e32 v28, v28
	s_nop 0
	v_mul_f32_e32 v29, 0x45800000, v28
	v_cndmask_b32_e32 v28, v28, v29, vcc
	v_mul_f32_e32 v25, v25, v28
	v_mul_f32_e32 v24, v24, v28
	s_waitcnt vmcnt(6)
	v_mul_f32_e32 v28, v23, v25
	v_mul_f32_e32 v24, v22, v24
	v_pk_mul_f32 v[28:29], v[16:17], v[28:29] op_sel:[1,0] op_sel_hi:[0,0]
	v_pk_fma_f32 v[32:33], v[16:17], v[24:25], v[28:29] neg_lo:[0,0,1] neg_hi:[0,0,1]
	v_pk_fma_f32 v[24:25], v[16:17], v[24:25], v[28:29] op_sel_hi:[1,0,1]
	s_nop 0
	v_cvt_pk_bf16_f32 v24, v32, v25
	global_store_dword v[34:35], v24, off offset:1152 sc1
.LBB0_980:
	s_or_b64 exec, exec, s[34:35]
	s_waitcnt vmcnt(7)
	v_cvt_pk_bf16_f32 v24, v59, s0
	s_and_b64 vcc, exec, s[10:11]
	global_store_short v[38:39], v24, off offset:768 sc1
	s_cbranch_vccnz .LBB0_984
	v_mul_f32_e32 v24, v21, v21
	v_fmac_f32_e32 v24, v20, v20
	s_nop 1
	v_add_f32_dpp v24, v24, v24 quad_perm:[1,0,3,2] row_mask:0xf bank_mask:0xf bound_ctrl:1
	s_nop 1
	v_add_f32_dpp v24, v24, v24 quad_perm:[2,3,0,1] row_mask:0xf bank_mask:0xf bound_ctrl:1
	s_nop 1
	v_add_f32_dpp v24, v24, v24 row_half_mirror row_mask:0xf bank_mask:0xf bound_ctrl:1
	s_nop 1
	v_add_f32_dpp v24, v24, v24 row_mirror row_mask:0xf bank_mask:0xf bound_ctrl:1
	s_nop 0
	v_readlane_b32 s34, v24, 0
	v_readlane_b32 s12, v24, 16
	v_readlane_b32 s35, v24, 32
	v_readlane_b32 s19, v24, 48
	s_and_saveexec_b64 s[10:11], s[2:3]
	s_cbranch_execz .LBB0_983
	v_mov_b32_e32 v24, s12
	v_mov_b32_e32 v25, s19
	v_pk_add_f32 v[24:25], s[34:35], v[24:25]
	s_nop 0
	v_add_f32_e32 v24, v24, v25
	v_fmamk_f32 v24, v24, 0x3c2aaaab, v56
	v_mul_f32_e32 v25, 0x4b800000, v24
	v_cmp_gt_f32_e32 vcc, s15, v24
	s_nop 1
	v_cndmask_b32_e32 v24, v24, v25, vcc
	v_rsq_f32_e32 v24, v24
	s_nop 0
	v_mul_f32_e32 v25, 0x45800000, v24
	v_cndmask_b32_e32 v24, v24, v25, vcc
	v_mul_f32_e32 v21, v21, v24
	v_mul_f32_e32 v20, v20, v24
	v_mul_f32_e32 v24, v27, v21
	v_mul_f32_e32 v20, v26, v20
	v_pk_mul_f32 v[24:25], v[16:17], v[24:25] op_sel:[1,0] op_sel_hi:[0,0]
	v_pk_fma_f32 v[26:27], v[16:17], v[20:21], v[24:25] neg_lo:[0,0,1] neg_hi:[0,0,1]
	v_pk_fma_f32 v[20:21], v[16:17], v[20:21], v[24:25] op_sel_hi:[1,0,1]
	s_nop 0
	v_mov_b32_e32 v27, v21
	v_pk_mul_f32 v[20:21], v[26:27], s[28:29] op_sel_hi:[1,0]
	s_nop 0
	v_cvt_pk_bf16_f32 v24, v20, v21
	v_add_co_u32_e32 v20, vcc, 0xabe8000, v30
	s_nop 1
	v_addc_co_u32_e32 v21, vcc, 0, v31, vcc
	global_store_dword v[20:21], v24, off offset:1344 sc1

.LBB0_984:
	v_mul_f32_e32 v20, v19, v19
	v_fmac_f32_e32 v20, v18, v18
	s_nop 1
	v_add_f32_dpp v20, v20, v20 quad_perm:[1,0,3,2] row_mask:0xf bank_mask:0xf bound_ctrl:1
	s_nop 1
	v_add_f32_dpp v20, v20, v20 quad_perm:[2,3,0,1] row_mask:0xf bank_mask:0xf bound_ctrl:1
	s_nop 1
	v_add_f32_dpp v20, v20, v20 row_half_mirror row_mask:0xf bank_mask:0xf bound_ctrl:1
	s_nop 1
	v_add_f32_dpp v20, v20, v20 row_mirror row_mask:0xf bank_mask:0xf bound_ctrl:1
	s_nop 0
	v_readlane_b32 s34, v20, 0
	v_readlane_b32 s12, v20, 16
	v_readlane_b32 s35, v20, 32
	v_readlane_b32 s19, v20, 48
	s_and_saveexec_b64 s[10:11], s[2:3]
	s_cbranch_execz .LBB0_890
	v_mov_b32_e32 v20, s12
	v_mov_b32_e32 v21, s19
	v_pk_add_f32 v[20:21], s[34:35], v[20:21]
	s_nop 0
	v_add_f32_e32 v20, v20, v21
	v_fmamk_f32 v20, v20, 0x3c2aaaab, v56
	v_mul_f32_e32 v21, 0x4b800000, v20
	v_cmp_gt_f32_e32 vcc, s15, v20
	s_nop 1
	v_cndmask_b32_e32 v20, v20, v21, vcc
	v_rsq_f32_e32 v20, v20
	s_nop 0
	v_mul_f32_e32 v21, 0x45800000, v20
	v_cndmask_b32_e32 v20, v20, v21, vcc
	v_mul_f32_e32 v19, v19, v20
	v_mul_f32_e32 v18, v18, v20
	s_waitcnt vmcnt(7)
	v_mul_f32_e32 v20, v23, v19
	v_mul_f32_e32 v18, v22, v18
	v_pk_mul_f32 v[20:21], v[16:17], v[20:21] op_sel:[1,0] op_sel_hi:[0,0]
	v_pk_fma_f32 v[22:23], v[16:17], v[18:19], v[20:21] neg_lo:[0,0,1] neg_hi:[0,0,1]
	v_pk_fma_f32 v[16:17], v[16:17], v[18:19], v[20:21] op_sel_hi:[1,0,1]
	s_nop 0
	v_cvt_pk_bf16_f32 v16, v22, v17
	global_store_dword v[34:35], v16, off offset:1344 sc1
	s_branch .LBB0_890

.LBB0_1075:
	ds_read_b128 v[18:21], v3
	s_add_i32 s40, s40, -1
	v_add_u32_e32 v3, s36, v3
	s_cmp_eq_u32 s40, 0
	s_waitcnt lgkmcnt(0)
	v_pk_add_f32 v[10:11], v[10:11], v[20:21]
	v_pk_add_f32 v[8:9], v[8:9], v[18:19]
	s_cbranch_scc0 .LBB0_1075
	s_add_i32 s40, s37, s8
	v_lshl_add_u32 v18, s40, 4, v12
	v_mov_b32_e32 v3, v2
	v_pk_mul_f32 v[10:11], v[2:3], v[10:11]
	v_pk_mul_f32 v[8:9], v[4:5], v[8:9]
	v_ashrrev_i32_e32 v19, 31, v18
	v_cvt_pk_bf16_f32 v8, v8, v9
	v_cvt_pk_bf16_f32 v9, v10, v11
	v_lshl_add_u64 v[10:11], v[18:19], 1, v[6:7]
	global_store_dwordx2 v[10:11], v[8:9], off sc1
	v_mov_b32_e32 v8, 0
	v_mov_b32_e32 v3, v14
	s_mov_b32 s41, s6
	v_mov_b32_e32 v9, v8
	v_mov_b32_e32 v10, v8
	v_mov_b32_e32 v11, v8
.LBB0_1077:
	ds_read_b128 v[18:21], v3
	s_add_i32 s41, s41, -1
	v_add_u32_e32 v3, s36, v3
	s_cmp_lg_u32 s41, 0
	s_waitcnt lgkmcnt(0)
	v_pk_add_f32 v[10:11], v[10:11], v[20:21]
	v_pk_add_f32 v[8:9], v[8:9], v[18:19]
	s_cbranch_scc1 .LBB0_1077
	s_lshl_b32 s40, s40, 4
	v_add3_u32 v18, s40, 16, v12
	v_mov_b32_e32 v3, v2
	v_pk_mul_f32 v[10:11], v[2:3], v[10:11]
	v_pk_mul_f32 v[8:9], v[4:5], v[8:9]
	v_ashrrev_i32_e32 v19, 31, v18
	v_cvt_pk_bf16_f32 v8, v8, v9
	v_cvt_pk_bf16_f32 v9, v10, v11
	v_lshl_add_u64 v[10:11], v[18:19], 1, v[6:7]
	global_store_dwordx2 v[10:11], v[8:9], off sc1
	v_mov_b32_e32 v8, 0
	v_mov_b32_e32 v3, v15
	s_mov_b32 s41, s6
	v_mov_b32_e32 v9, v8
	v_mov_b32_e32 v10, v8
	v_mov_b32_e32 v11, v8
.LBB0_1079:
	ds_read_b128 v[18:21], v3
	s_add_i32 s41, s41, -1
	v_add_u32_e32 v3, s36, v3
	s_cmp_lg_u32 s41, 0
	s_waitcnt lgkmcnt(0)
	v_pk_add_f32 v[10:11], v[10:11], v[20:21]
	v_pk_add_f32 v[8:9], v[8:9], v[18:19]
	s_cbranch_scc1 .LBB0_1079
	v_add3_u32 v18, s40, 32, v12
	v_mov_b32_e32 v3, v2
	v_pk_mul_f32 v[10:11], v[2:3], v[10:11]
	v_pk_mul_f32 v[8:9], v[4:5], v[8:9]
	v_ashrrev_i32_e32 v19, 31, v18
	v_cvt_pk_bf16_f32 v8, v8, v9
	v_cvt_pk_bf16_f32 v9, v10, v11
	v_lshl_add_u64 v[10:11], v[18:19], 1, v[6:7]
	global_store_dwordx2 v[10:11], v[8:9], off sc1
	v_mov_b32_e32 v8, 0
	v_mov_b32_e32 v3, v16
	s_mov_b32 s41, s6
	v_mov_b32_e32 v9, v8
	v_mov_b32_e32 v10, v8
	v_mov_b32_e32 v11, v8
.LBB0_1081:
	ds_read_b128 v[18:21], v3
	s_add_i32 s41, s41, -1
	v_add_u32_e32 v3, s36, v3
	s_cmp_lg_u32 s41, 0
	s_waitcnt lgkmcnt(0)
	v_pk_add_f32 v[10:11], v[10:11], v[20:21]
	v_pk_add_f32 v[8:9], v[8:9], v[18:19]
	s_cbranch_scc1 .LBB0_1081
	v_add3_u32 v18, s40, 48, v12
	v_mov_b32_e32 v3, v2
	v_pk_mul_f32 v[10:11], v[2:3], v[10:11]
	v_pk_mul_f32 v[8:9], v[4:5], v[8:9]
	v_ashrrev_i32_e32 v19, 31, v18
	s_add_i32 s37, s37, 4
	v_cvt_pk_bf16_f32 v8, v8, v9
	v_cvt_pk_bf16_f32 v9, v10, v11
	v_lshl_add_u64 v[10:11], v[18:19], 1, v[6:7]
	v_add_u32_e32 v13, 0x1000, v13
	v_add_u32_e32 v14, 0x1000, v14
	v_add_u32_e32 v15, 0x1000, v15
	s_cmp_lg_u32 s37, s11
	v_add_u32_e32 v16, 0x1000, v16
	global_store_dwordx2 v[10:11], v[8:9], off sc1
	s_cbranch_scc1 .LBB0_1074

.LBB0_1086:
	ds_read_b128 v[14:17], v3
	s_add_i32 s41, s41, -1
	v_add_u32_e32 v3, s37, v3
	s_cmp_lg_u32 s41, 0
	s_waitcnt lgkmcnt(0)
	v_pk_add_f32 v[10:11], v[10:11], v[16:17]
	v_pk_add_f32 v[8:9], v[8:9], v[14:15]
	s_cbranch_scc1 .LBB0_1086
	s_add_i32 s41, s11, s8
	v_lshl_add_u32 v14, s41, 4, v12
	v_mov_b32_e32 v3, v2
	v_pk_mul_f32 v[10:11], v[2:3], v[10:11]
	v_pk_mul_f32 v[8:9], v[4:5], v[8:9]
	v_ashrrev_i32_e32 v15, 31, v14
	s_add_i32 s11, s11, 1
	s_add_i32 s40, s40, 1
	v_cvt_pk_bf16_f32 v8, v8, v9
	v_cvt_pk_bf16_f32 v9, v10, v11
	v_lshl_add_u64 v[10:11], v[14:15], 1, v[6:7]
	s_cmp_lg_u32 s40, s36
	v_add_u32_e32 v13, 0x400, v13
	global_store_dwordx2 v[10:11], v[8:9], off sc1
	s_cbranch_scc1 .LBB0_1085

.LBB0_1092:
	ds_read_b128 v[16:19], v14
	s_add_i32 s11, s11, -1
	v_add_u32_e32 v14, s9, v14
	s_cmp_lg_u32 s11, 0
	s_waitcnt lgkmcnt(0)
	v_pk_add_f32 v[10:11], v[10:11], v[18:19]
	v_pk_add_f32 v[8:9], v[8:9], v[16:17]
	s_cbranch_scc1 .LBB0_1092
	s_add_i32 s11, s10, s8
	v_lshl_add_u32 v14, s11, 4, v12
	v_pk_mul_f32 v[10:11], v[4:5], v[10:11]
	v_pk_mul_f32 v[8:9], v[2:3], v[8:9]
	v_ashrrev_i32_e32 v15, 31, v14
	s_add_i32 s10, s10, 1
	v_cvt_pk_bf16_f32 v8, v8, v9
	v_cvt_pk_bf16_f32 v9, v10, v11
	v_lshl_add_u64 v[10:11], v[14:15], 1, v[6:7]
	s_cmp_eq_u32 s10, s28
	v_add_u32_e32 v13, 0x400, v13
	global_store_dwordx2 v[10:11], v[8:9], off sc1
	s_cbranch_scc0 .LBB0_1091
	s_barrier
	s_branch .LBB0_1044

.LBB0_1097:
	s_or_b64 exec, exec, s[34:35]
	s_waitcnt lgkmcnt(0)
	s_barrier
	ds_read_b64 v[10:11], v23 offset:280
	v_or_b32_e32 v84, s73, v1
	v_ashrrev_i32_e32 v85, 31, v84
	s_lshl_b32 s42, s36, 2
	s_mov_b32 s67, s43
	s_waitcnt lgkmcnt(0)
	v_readfirstlane_b32 s34, v10
	v_readfirstlane_b32 s35, v11
	v_lshlrev_b64 v[10:11], 13, v[84:85]
	s_add_u32 s37, s34, s42
	v_lshl_add_u64 v[10:11], s[44:45], 0, v[10:11]
	s_addc_u32 s64, s35, 0
	s_lshl_b32 s66, s51, 2
	v_lshl_add_u64 v[10:11], v[10:11], 0, s[42:43]
	v_lshlrev_b32_e32 v30, 2, v98
	v_mov_b32_e32 v31, v23
	v_lshl_add_u64 v[10:11], v[10:11], 0, s[66:67]
	v_lshl_add_u64 v[10:11], v[10:11], 0, v[30:31]
	v_add_co_u32_e64 v10, s[34:35], s72, v10
	v_mov_b64_e32 v[32:33], s[54:55]
	s_nop 0
	v_addc_co_u32_e64 v11, s[34:35], 0, v11, s[34:35]
	global_load_dwordx4 v[80:83], v[10:11], off offset:1664
	s_mov_b64 s[98:99], 0x20000
	v_lshl_add_u64 v[200:201], v[10:11], 0, s[98:99]
	v_lshl_add_u64 v[202:203], v[200:201], 0, s[98:99]
	v_lshl_add_u64 v[204:205], v[202:203], 0, s[98:99]
	global_load_dwordx4 v[208:211], v[200:201], off offset:1664
	global_load_dwordx4 v[212:215], v[202:203], off offset:1664
	global_load_dwordx4 v[216:219], v[204:205], off offset:1664
	s_add_u32 s34, s37, s66
	s_addc_u32 s35, s64, 0
	v_or_b32_e32 v104, s73, v66
	s_nop 0
	global_load_dwordx4 v[10:13], v30, s[34:35]
	ds_read2st64_b32 v[86:87], v65 offset1:1
	ds_read2st64_b32 v[88:89], v65 offset0:2 offset1:3
	ds_read2st64_b32 v[90:91], v65 offset0:4 offset1:5
	ds_read2st64_b32 v[92:93], v65 offset0:6 offset1:7
	ds_read2st64_b32 v[94:95], v67 offset1:1
	ds_read2st64_b32 v[96:97], v67 offset0:2 offset1:3
	ds_read2st64_b32 v[100:101], v67 offset0:4 offset1:5
	ds_read2st64_b32 v[102:103], v67 offset0:6 offset1:7
	s_waitcnt lgkmcnt(7)
	v_mov_b32_e32 v109, v86
	s_waitcnt lgkmcnt(3)
	v_mov_b32_e32 v108, v94
	v_mov_b32_e32 v86, v95
	s_waitcnt lgkmcnt(2)
	v_mov_b32_e32 v94, v96
	v_mov_b32_e32 v95, v88
	v_mov_b32_e32 v88, v97
	s_waitcnt lgkmcnt(1)
	v_mov_b32_e32 v96, v100
	v_mov_b32_e32 v97, v90
	v_mov_b32_e32 v90, v101
	s_waitcnt lgkmcnt(0)
	v_mov_b32_e32 v100, v102
	v_mov_b32_e32 v101, v92
	v_mov_b32_e32 v92, v103
	v_pk_add_f32 v[102:103], v[108:109], 0 op_sel_hi:[1,0]
	v_lshlrev_b64 v[84:85], 11, v[84:85]
	v_pk_add_f32 v[86:87], v[102:103], v[86:87]
	s_mov_b32 s37, s43
	v_pk_add_f32 v[86:87], v[86:87], v[94:95]
	v_ashrrev_i32_e32 v105, 31, v104
	v_pk_add_f32 v[86:87], v[86:87], v[88:89]
	v_lshl_add_u64 v[84:85], s[38:39], 0, v[84:85]
	v_pk_add_f32 v[86:87], v[86:87], v[96:97]
	s_lshl_b32 s36, s36, 1
	v_pk_add_f32 v[86:87], v[86:87], v[90:91]
	s_mov_b32 s65, s43
	v_pk_add_f32 v[86:87], v[86:87], v[100:101]
	v_lshlrev_b64 v[106:107], 13, v[104:105]
	v_pk_add_f32 v[86:87], v[86:87], v[92:93]
	s_lshl_b32 s64, s51, 1
	v_pk_fma_f32 v[86:87], v[86:87], s[52:53], v[32:33] op_sel_hi:[1,0,0]
	v_lshl_add_u64 v[84:85], v[84:85], 0, s[36:37]
	v_mul_f32_e32 v27, 0x4b800000, v87
	v_cmp_gt_f32_e64 s[34:35], s69, v87
	v_lshlrev_b32_e32 v28, 1, v98
	v_mov_b32_e32 v29, v23
	v_cndmask_b32_e64 v27, v87, v27, s[34:35]
	v_rsq_f32_e32 v27, v27
	v_lshl_add_u64 v[106:107], s[44:45], 0, v[106:107]
	v_lshl_add_u64 v[84:85], v[84:85], 0, s[64:65]
	v_lshl_add_u64 v[106:107], v[106:107], 0, s[42:43]
	v_lshl_add_u64 v[84:85], v[84:85], 0, v[28:29]
	v_or_b32_e32 v94, s73, v70
	v_ashrrev_i32_e32 v95, 31, v94
	v_lshlrev_b64 v[96:97], 13, v[94:95]
	v_lshl_add_u64 v[96:97], s[44:45], 0, v[96:97]
	v_lshl_add_u64 v[96:97], v[96:97], 0, s[42:43]
	s_add_i32 s40, s40, s56
	v_lshl_add_u64 v[24:25], v[24:25], 0, s[46:47]
	s_waitcnt vmcnt(4)
	v_mul_f32_e32 v79, 0xbfb8aa3b, v80
	v_mul_f32_e32 v87, 0xbfb8aa3b, v81
	v_mul_f32_e32 v88, 0xbfb8aa3b, v82
	v_mul_f32_e32 v89, 0xbfb8aa3b, v83
	v_exp_f32_e32 v79, v79
	v_exp_f32_e32 v87, v87
	v_exp_f32_e32 v88, v88
	v_exp_f32_e32 v89, v89
	v_add_f32_e32 v79, 1.0, v79
	v_add_f32_e32 v87, 1.0, v87
	v_add_f32_e32 v90, 1.0, v88
	v_add_f32_e32 v91, 1.0, v89
	v_rcp_f32_e32 v88, v79
	v_rcp_f32_e32 v89, v87
	v_rcp_f32_e32 v90, v90
	v_rcp_f32_e32 v91, v91
	v_mul_f32_e32 v79, 0x45800000, v27
	v_pk_mul_f32 v[80:81], v[80:81], v[88:89]
	v_cndmask_b32_e64 v92, v27, v79, s[34:35]
	v_pk_mul_f32 v[82:83], v[82:83], v[90:91]
	v_pk_mul_f32 v[18:19], v[18:19], v[80:81]
	v_pk_mul_f32 v[20:21], v[20:21], v[82:83]
	v_pk_mul_f32 v[18:19], v[92:93], v[18:19] op_sel_hi:[0,1]
	v_pk_mul_f32 v[20:21], v[92:93], v[20:21] op_sel_hi:[0,1]
	s_waitcnt vmcnt(0)
	v_pk_mul_f32 v[18:19], v[10:11], v[18:19]
	v_pk_mul_f32 v[20:21], v[12:13], v[20:21]
	v_cvt_pk_bf16_f32 v18, v18, v19
	v_cvt_pk_bf16_f32 v19, v20, v21
	global_store_dwordx2 v[84:85], v[18:19], off offset:1024 sc1
	v_lshl_add_u64 v[18:19], v[106:107], 0, s[66:67]
	v_lshl_add_u64 v[18:19], v[18:19], 0, v[30:31]
	v_add_co_u32_e64 v18, s[34:35], s72, v18
	v_or_b32_e32 v80, s73, v68
	s_nop 0
	v_addc_co_u32_e64 v19, s[34:35], 0, v19, s[34:35]
	v_mov_b64_e32 v[18:19], v[208:209]
	v_mov_b64_e32 v[20:21], v[210:211]
	v_ashrrev_i32_e32 v81, 31, v80
	v_lshlrev_b64 v[84:85], 13, v[80:81]
	v_lshl_add_u64 v[84:85], s[44:45], 0, v[84:85]
	v_lshl_add_u64 v[84:85], v[84:85], 0, s[42:43]
	v_lshl_add_u64 v[84:85], v[84:85], 0, s[66:67]
	v_lshl_add_u64 v[84:85], v[84:85], 0, v[30:31]
	v_add_co_u32_e64 v84, s[34:35], s72, v84
	v_mul_f32_e32 v27, 0x4b800000, v86
	s_nop 0
	v_addc_co_u32_e64 v85, s[34:35], 0, v85, s[34:35]
	v_cmp_gt_f32_e64 s[34:35], s69, v86
	v_lshlrev_b64 v[82:83], 11, v[104:105]
	v_lshl_add_u64 v[82:83], s[38:39], 0, v[82:83]
	v_cndmask_b32_e64 v27, v86, v27, s[34:35]
	v_rsq_f32_e32 v27, v27
	v_lshl_add_u64 v[82:83], v[82:83], 0, s[36:37]
	v_lshl_add_u64 v[82:83], v[82:83], 0, s[64:65]
	v_lshl_add_u64 v[82:83], v[82:83], 0, v[28:29]
	v_lshlrev_b64 v[80:81], 11, v[80:81]
	v_lshl_add_u64 v[80:81], s[38:39], 0, v[80:81]
	v_mul_f32_e32 v79, 0xbfb8aa3b, v18
	v_mul_f32_e32 v86, 0xbfb8aa3b, v19
	v_mul_f32_e32 v87, 0xbfb8aa3b, v20
	v_mul_f32_e32 v88, 0xbfb8aa3b, v21
	v_exp_f32_e32 v79, v79
	v_exp_f32_e32 v86, v86
	v_exp_f32_e32 v87, v87
	v_exp_f32_e32 v88, v88
	v_add_f32_e32 v79, 1.0, v79
	v_add_f32_e32 v89, 1.0, v86
	v_add_f32_e32 v90, 1.0, v87
	v_add_f32_e32 v91, 1.0, v88
	v_rcp_f32_e32 v86, v79
	v_rcp_f32_e32 v87, v89
	v_rcp_f32_e32 v88, v90
	v_rcp_f32_e32 v89, v91
	v_mul_f32_e32 v79, 0x45800000, v27
	v_pk_mul_f32 v[18:19], v[18:19], v[86:87]
	v_cndmask_b32_e64 v90, v27, v79, s[34:35]
	v_pk_mul_f32 v[20:21], v[20:21], v[88:89]
	v_pk_mul_f32 v[14:15], v[14:15], v[18:19]
	v_pk_mul_f32 v[16:17], v[16:17], v[20:21]
	v_pk_mul_f32 v[14:15], v[90:91], v[14:15] op_sel_hi:[0,1]
	v_pk_mul_f32 v[16:17], v[90:91], v[16:17] op_sel_hi:[0,1]
	v_pk_mul_f32 v[14:15], v[10:11], v[14:15]
	v_pk_mul_f32 v[16:17], v[12:13], v[16:17]
	v_cvt_pk_bf16_f32 v14, v14, v15
	v_cvt_pk_bf16_f32 v15, v16, v17
	global_store_dwordx2 v[82:83], v[14:15], off offset:1024 sc1
	v_mov_b64_e32 v[14:15], v[212:213]
	v_mov_b64_e32 v[16:17], v[214:215]
	ds_read2st64_b32 v[18:19], v69 offset1:1
	ds_read2st64_b32 v[20:21], v69 offset0:2 offset1:3
	ds_read2st64_b32 v[82:83], v69 offset0:4 offset1:5
	ds_read2st64_b32 v[84:85], v69 offset0:6 offset1:7
	ds_read2st64_b32 v[86:87], v71 offset1:1
	ds_read2st64_b32 v[88:89], v71 offset0:2 offset1:3
	ds_read2st64_b32 v[90:91], v71 offset0:4 offset1:5
	ds_read2st64_b32 v[92:93], v71 offset0:6 offset1:7
	s_waitcnt lgkmcnt(7)
	v_mov_b32_e32 v101, v18
	s_waitcnt lgkmcnt(3)
	v_mov_b32_e32 v100, v86
	v_mov_b32_e32 v18, v87
	s_waitcnt lgkmcnt(2)
	v_mov_b32_e32 v86, v88
	v_mov_b32_e32 v87, v20
	v_mov_b32_e32 v20, v89
	s_waitcnt lgkmcnt(1)
	v_mov_b32_e32 v88, v90
	v_mov_b32_e32 v89, v82
	v_mov_b32_e32 v82, v91
	s_waitcnt lgkmcnt(0)
	v_mov_b32_e32 v90, v92
	v_mov_b32_e32 v91, v84
	v_mov_b32_e32 v84, v93
	v_pk_add_f32 v[92:93], v[100:101], 0 op_sel_hi:[1,0]
	v_mul_f32_e32 v79, 0xbfb8aa3b, v17
	v_pk_add_f32 v[18:19], v[92:93], v[18:19]
	v_exp_f32_e32 v79, v79
	v_pk_add_f32 v[18:19], v[18:19], v[86:87]
	v_lshl_add_u64 v[86:87], v[96:97], 0, s[66:67]
	v_pk_add_f32 v[18:19], v[18:19], v[20:21]
	v_lshl_add_u64 v[20:21], v[86:87], 0, v[30:31]
	v_pk_add_f32 v[18:19], v[18:19], v[88:89]
	v_add_co_u32_e64 v20, s[34:35], s72, v20
	v_pk_add_f32 v[18:19], v[18:19], v[82:83]
	s_nop 0
	v_addc_co_u32_e64 v21, s[34:35], 0, v21, s[34:35]
	v_pk_add_f32 v[18:19], v[18:19], v[90:91]
	v_lshl_add_u64 v[30:31], v[80:81], 0, s[36:37]
	v_pk_add_f32 v[18:19], v[18:19], v[84:85]
	v_add_f32_e32 v79, 1.0, v79
	v_pk_fma_f32 v[18:19], v[18:19], s[52:53], v[32:33] op_sel_hi:[1,0,0]
	v_mul_f32_e32 v32, 0xbfb8aa3b, v15
	v_mul_f32_e32 v27, 0x4b800000, v19
	v_cmp_gt_f32_e64 s[34:35], s69, v19
	v_mul_f32_e32 v33, 0xbfb8aa3b, v16
	v_exp_f32_e32 v32, v32
	v_cndmask_b32_e64 v19, v19, v27, s[34:35]
	v_mul_f32_e32 v27, 0xbfb8aa3b, v14
	v_exp_f32_e32 v27, v27
	v_exp_f32_e32 v33, v33
	v_add_f32_e32 v80, 1.0, v32
	v_rsq_f32_e32 v19, v19
	v_add_f32_e32 v27, 1.0, v27
	v_add_f32_e32 v81, 1.0, v33
	v_rcp_f32_e32 v32, v27
	v_rcp_f32_e32 v33, v80
	v_rcp_f32_e32 v80, v81
	v_rcp_f32_e32 v81, v79
	v_mul_f32_e32 v27, 0x45800000, v19
	v_pk_mul_f32 v[14:15], v[14:15], v[32:33]
	v_cndmask_b32_e64 v82, v19, v27, s[34:35]
	v_pk_mul_f32 v[16:17], v[16:17], v[80:81]
	v_pk_mul_f32 v[6:7], v[6:7], v[14:15]
	v_pk_mul_f32 v[8:9], v[8:9], v[16:17]
	v_pk_mul_f32 v[6:7], v[82:83], v[6:7] op_sel_hi:[0,1]
	v_pk_mul_f32 v[8:9], v[82:83], v[8:9] op_sel_hi:[0,1]
	v_lshl_add_u64 v[30:31], v[30:31], 0, s[64:65]
	v_pk_mul_f32 v[6:7], v[10:11], v[6:7]
	v_pk_mul_f32 v[8:9], v[12:13], v[8:9]
	v_lshl_add_u64 v[30:31], v[30:31], 0, v[28:29]
	v_cvt_pk_bf16_f32 v6, v6, v7
	v_cvt_pk_bf16_f32 v7, v8, v9
	global_store_dwordx2 v[30:31], v[6:7], off offset:1024 sc1
	v_mov_b64_e32 v[6:7], v[216:217]
	v_mov_b64_e32 v[8:9], v[218:219]
	v_mul_f32_e32 v16, 0x4b800000, v18
	v_cmp_gt_f32_e64 s[34:35], s69, v18
	v_lshlrev_b64 v[14:15], 11, v[94:95]
	v_lshl_add_u64 v[14:15], s[38:39], 0, v[14:15]
	v_cndmask_b32_e64 v16, v18, v16, s[34:35]
	v_rsq_f32_e32 v20, v16
	v_lshl_add_u64 v[14:15], v[14:15], 0, s[36:37]
	s_add_i32 s53, s53, s55
	v_lshl_add_u64 v[14:15], v[14:15], 0, s[64:65]
	v_mul_f32_e32 v21, 0x45800000, v20
	v_cndmask_b32_e64 v20, v20, v21, s[34:35]
	s_cmpk_lt_i32 s40, 0x180
	v_lshl_add_u64 v[14:15], v[14:15], 0, v[28:29]
	v_mul_f32_e32 v16, 0xbfb8aa3b, v6
	v_mul_f32_e32 v17, 0xbfb8aa3b, v7
	v_mul_f32_e32 v18, 0xbfb8aa3b, v8
	v_mul_f32_e32 v19, 0xbfb8aa3b, v9
	v_exp_f32_e32 v16, v16
	v_exp_f32_e32 v17, v17
	v_exp_f32_e32 v18, v18
	v_exp_f32_e32 v19, v19
	v_add_f32_e32 v16, 1.0, v16
	v_add_f32_e32 v17, 1.0, v17
	v_add_f32_e32 v18, 1.0, v18
	v_add_f32_e32 v19, 1.0, v19
	v_rcp_f32_e32 v16, v16
	v_rcp_f32_e32 v17, v17
	v_rcp_f32_e32 v18, v18
	v_rcp_f32_e32 v19, v19
	v_pk_mul_f32 v[6:7], v[6:7], v[16:17]
	s_nop 0
	v_pk_mul_f32 v[2:3], v[2:3], v[6:7]
	v_pk_mul_f32 v[8:9], v[8:9], v[18:19]
	v_pk_mul_f32 v[2:3], v[20:21], v[2:3] op_sel_hi:[0,1]
	v_pk_mul_f32 v[4:5], v[4:5], v[8:9]
	v_pk_mul_f32 v[2:3], v[10:11], v[2:3]
	v_pk_mul_f32 v[4:5], v[20:21], v[4:5] op_sel_hi:[0,1]
	v_pk_mul_f32 v[4:5], v[12:13], v[4:5]
	v_cvt_pk_bf16_f32 v2, v2, v3
	v_cvt_pk_bf16_f32 v3, v4, v5
	global_store_dwordx2 v[14:15], v[2:3], off offset:1024 sc1
	s_barrier
	s_cbranch_scc0 .LBB0_1106
